# fox unit boundary: the O stores of a finished unit are no longer waited for (vmcnt) at the unit-end and loop-head barriers; only the first-ticket atomic is waited
# baseline (speedup 1.0000x reference)
.Lfox_pf_skip:
	s_or_b64 exec, exec, s[2:3]
	s_mov_b32 s100, 1
	s_waitcnt lgkmcnt(0)
	s_waitcnt lgkmcnt(0)
	ds_read_b128 v[34:37], v226
	ds_read_b128 v[52:55], v226 offset:32
	v_readlane_b32 s36, v253, 20
	v_readlane_b32 s44, v253, 28
	v_readlane_b32 s45, v253, 29
	s_waitcnt lgkmcnt(1)
	v_rcp_f32_e32 v34, v34
	v_readlane_b32 s37, v253, 21
	v_readlane_b32 s38, v253, 22
	v_readlane_b32 s39, v253, 23
	v_mul_f32_e32 v47, v2, v34
	v_rcp_f32_e32 v2, v35
	v_mul_f32_e32 v46, v18, v34
	v_mul_f32_e32 v49, v46, v46
	v_fmac_f32_e32 v49, v47, v47
	v_mul_f32_e32 v45, v3, v2
	v_mul_f32_e32 v44, v19, v2
	v_rcp_f32_e32 v2, v36
	v_mul_f32_e32 v50, v44, v44
	v_fmac_f32_e32 v50, v45, v45
	v_readlane_b32 s40, v253, 24
	v_mul_f32_e32 v43, v4, v2
	v_mul_f32_e32 v42, v20, v2
	v_rcp_f32_e32 v2, v37
	v_mul_f32_e32 v51, v42, v42
	v_fmac_f32_e32 v51, v43, v43
	v_readlane_b32 s41, v253, 25
	v_mul_f32_e32 v41, v5, v2
	v_mul_f32_e32 v40, v21, v2
	s_waitcnt lgkmcnt(0)
	v_rcp_f32_e32 v2, v52
	v_mul_f32_e32 v56, v40, v40
	v_fmac_f32_e32 v56, v41, v41
	v_readlane_b32 s42, v253, 26
	v_mul_f32_e32 v39, v6, v2
	v_mul_f32_e32 v38, v22, v2
	v_rcp_f32_e32 v2, v53
	v_mul_f32_e32 v52, v38, v38
	v_fmac_f32_e32 v52, v39, v39
	v_readlane_b32 s43, v253, 27
	v_mul_f32_e32 v37, v7, v2
	v_mul_f32_e32 v36, v23, v2
	v_rcp_f32_e32 v2, v54
	v_mul_f32_e32 v53, v36, v36
	v_fmac_f32_e32 v53, v37, v37
	v_readlane_b32 s46, v253, 30
	v_mul_f32_e32 v35, v8, v2
	v_mul_f32_e32 v34, v24, v2
	v_rcp_f32_e32 v2, v55
	v_mul_f32_e32 v54, v34, v34
	v_fmac_f32_e32 v54, v35, v35
	v_readlane_b32 s47, v253, 31
	v_mul_f32_e32 v24, v9, v2
	v_mul_f32_e32 v23, v25, v2
	ds_read_b128 v[2:5], v226 offset:64
	v_mul_f32_e32 v25, v23, v23
	v_fmac_f32_e32 v25, v24, v24
	v_readlane_b32 s48, v253, 32
	v_readlane_b32 s49, v253, 33
	s_waitcnt lgkmcnt(0)
	v_rcp_f32_e32 v2, v2
	v_readlane_b32 s50, v253, 34
	v_readlane_b32 s51, v253, 35
	v_mul_f32_e32 v22, v10, v2
	v_mul_f32_e32 v21, v26, v2
	v_rcp_f32_e32 v2, v3
	v_mul_f32_e32 v55, v21, v21
	v_fmac_f32_e32 v55, v22, v22
	v_mul_f32_e32 v20, v11, v2
	v_mul_f32_e32 v19, v27, v2
	v_rcp_f32_e32 v2, v4
	v_mul_f32_e32 v57, v19, v19
	v_fmac_f32_e32 v57, v20, v20
	v_mul_f32_e32 v18, v12, v2
	v_mul_f32_e32 v11, v28, v2
	v_rcp_f32_e32 v2, v5
	v_mul_f32_e32 v58, v11, v11
	v_fmac_f32_e32 v58, v18, v18
	v_mul_f32_e32 v6, v29, v2
	ds_read_b128 v[26:29], v226 offset:96
	v_mul_f32_e32 v7, v13, v2
	v_mul_f32_e32 v13, v6, v6
	v_fmac_f32_e32 v13, v7, v7
	s_waitcnt lgkmcnt(0)
	v_rcp_f32_e32 v2, v26
	v_xor_b32_e32 v26, 1, v240
	v_cmp_lt_i32_e32 vcc, v26, v48
	v_mul_f32_e32 v12, v14, v2
	v_mul_f32_e32 v10, v30, v2
	v_rcp_f32_e32 v2, v27
	v_cndmask_b32_e32 v26, v240, v26, vcc
	v_lshlrev_b32_e32 v26, 2, v26
	v_mul_f32_e32 v14, v10, v10
	v_mul_f32_e32 v8, v31, v2
	ds_bpermute_b32 v31, v26, v52
	v_fmac_f32_e32 v14, v12, v12
	v_mul_f32_e32 v9, v15, v2
	v_rcp_f32_e32 v2, v28
	ds_bpermute_b32 v27, v26, v49
	s_waitcnt lgkmcnt(1)
	v_add_f32_e32 v31, v52, v31
	ds_bpermute_b32 v52, v26, v13
	v_mul_f32_e32 v15, v8, v8
	v_mul_f32_e32 v5, v16, v2
	v_mul_f32_e32 v4, v32, v2
	v_rcp_f32_e32 v2, v29
	s_waitcnt lgkmcnt(0)
	v_add_f32_e32 v13, v13, v52
	ds_bpermute_b32 v52, v26, v14
	v_fmac_f32_e32 v15, v9, v9
	v_add_f32_e32 v27, v49, v27
	ds_bpermute_b32 v28, v26, v50
	ds_bpermute_b32 v29, v26, v51
	ds_bpermute_b32 v49, v26, v25
	s_waitcnt lgkmcnt(3)
	v_add_f32_e32 v14, v14, v52
	ds_bpermute_b32 v52, v26, v15
	v_mul_f32_e32 v3, v17, v2
	v_mul_f32_e32 v2, v33, v2
	v_mul_f32_e32 v16, v4, v4
	v_mul_f32_e32 v17, v2, v2
	v_fmac_f32_e32 v16, v5, v5
	v_fmac_f32_e32 v17, v3, v3
	s_waitcnt lgkmcnt(3)
	v_add_f32_e32 v28, v50, v28
	s_waitcnt lgkmcnt(2)
	v_add_f32_e32 v29, v51, v29
	ds_bpermute_b32 v30, v26, v56
	ds_bpermute_b32 v32, v26, v53
	ds_bpermute_b32 v33, v26, v54
	s_waitcnt lgkmcnt(4)
	v_add_f32_e32 v25, v25, v49
	ds_bpermute_b32 v49, v26, v55
	ds_bpermute_b32 v50, v26, v57
	ds_bpermute_b32 v51, v26, v58
	s_waitcnt lgkmcnt(6)
	v_add_f32_e32 v15, v15, v52
	ds_bpermute_b32 v52, v26, v16
	ds_bpermute_b32 v26, v26, v17
	s_waitcnt lgkmcnt(7)
	v_add_f32_e32 v30, v56, v30
	s_waitcnt lgkmcnt(6)
	v_add_f32_e32 v32, v53, v32
	s_waitcnt lgkmcnt(5)
	v_add_f32_e32 v33, v54, v33
	s_waitcnt lgkmcnt(1)
	v_add_f32_e32 v16, v16, v52
	s_waitcnt lgkmcnt(0)
	v_add_f32_e32 v17, v17, v26
	v_xor_b32_e32 v26, 2, v240
	v_cmp_lt_i32_e32 vcc, v26, v48
	v_add_f32_e32 v49, v55, v49
	v_add_f32_e32 v50, v57, v50
	v_cndmask_b32_e32 v26, v240, v26, vcc
	v_lshlrev_b32_e32 v26, 2, v26
	ds_bpermute_b32 v52, v26, v27
	v_add_f32_e32 v51, v58, v51
	s_waitcnt lgkmcnt(0)
	v_add_f32_e32 v27, v27, v52
	ds_bpermute_b32 v52, v26, v28
	s_waitcnt lgkmcnt(0)
	v_add_f32_e32 v28, v28, v52
	ds_bpermute_b32 v52, v26, v29
	s_waitcnt lgkmcnt(0)
	v_add_f32_e32 v29, v29, v52
	ds_bpermute_b32 v52, v26, v30
	s_waitcnt lgkmcnt(0)
	v_add_f32_e32 v30, v30, v52
	ds_bpermute_b32 v52, v26, v31
	s_waitcnt lgkmcnt(0)
	v_add_f32_e32 v31, v31, v52
	ds_bpermute_b32 v52, v26, v32
	s_waitcnt lgkmcnt(0)
	v_add_f32_e32 v32, v32, v52
	ds_bpermute_b32 v52, v26, v33
	s_waitcnt lgkmcnt(0)
	v_add_f32_e32 v33, v33, v52
	ds_bpermute_b32 v52, v26, v25
	s_waitcnt lgkmcnt(0)
	v_add_f32_e32 v25, v25, v52
	ds_bpermute_b32 v52, v26, v49
	s_waitcnt lgkmcnt(0)
	v_add_f32_e32 v49, v49, v52
	ds_bpermute_b32 v52, v26, v50
	s_waitcnt lgkmcnt(0)
	v_add_f32_e32 v50, v50, v52
	ds_bpermute_b32 v52, v26, v51
	s_waitcnt lgkmcnt(0)
	v_add_f32_e32 v51, v51, v52
	ds_bpermute_b32 v52, v26, v13
	s_waitcnt lgkmcnt(0)
	v_add_f32_e32 v13, v13, v52
	ds_bpermute_b32 v52, v26, v14
	s_waitcnt lgkmcnt(0)
	v_add_f32_e32 v14, v14, v52
	ds_bpermute_b32 v52, v26, v15
	s_waitcnt lgkmcnt(0)
	v_add_f32_e32 v15, v15, v52
	ds_bpermute_b32 v52, v26, v16
	ds_bpermute_b32 v26, v26, v17
	s_waitcnt lgkmcnt(1)
	v_add_f32_e32 v16, v16, v52
	s_waitcnt lgkmcnt(0)
	v_add_f32_e32 v17, v17, v26
	v_xor_b32_e32 v26, 4, v240
	v_cmp_lt_i32_e32 vcc, v26, v48
	s_nop 1
	v_cndmask_b32_e32 v26, v240, v26, vcc
	v_lshlrev_b32_e32 v26, 2, v26
	ds_bpermute_b32 v52, v26, v27
	s_waitcnt lgkmcnt(0)
	v_add_f32_e32 v27, v27, v52
	ds_bpermute_b32 v52, v26, v28
	s_waitcnt lgkmcnt(0)
	v_add_f32_e32 v28, v28, v52
	ds_bpermute_b32 v52, v26, v29
	s_waitcnt lgkmcnt(0)
	v_add_f32_e32 v29, v29, v52
	ds_bpermute_b32 v52, v26, v30
	s_waitcnt lgkmcnt(0)
	v_add_f32_e32 v30, v30, v52
	ds_bpermute_b32 v52, v26, v31
	s_waitcnt lgkmcnt(0)
	v_add_f32_e32 v31, v31, v52
	ds_bpermute_b32 v52, v26, v32
	s_waitcnt lgkmcnt(0)
	v_add_f32_e32 v32, v32, v52
	ds_bpermute_b32 v52, v26, v33
	s_waitcnt lgkmcnt(0)
	v_add_f32_e32 v33, v33, v52
	ds_bpermute_b32 v52, v26, v25
	s_waitcnt lgkmcnt(0)
	v_add_f32_e32 v25, v25, v52
	ds_bpermute_b32 v52, v26, v49
	s_waitcnt lgkmcnt(0)
	v_add_f32_e32 v49, v49, v52
	ds_bpermute_b32 v52, v26, v50
	s_waitcnt lgkmcnt(0)
	v_add_f32_e32 v50, v50, v52
	ds_bpermute_b32 v52, v26, v51
	s_waitcnt lgkmcnt(0)
	v_add_f32_e32 v51, v51, v52
	ds_bpermute_b32 v52, v26, v13
	s_waitcnt lgkmcnt(0)
	v_add_f32_e32 v13, v13, v52
	ds_bpermute_b32 v52, v26, v14
	s_waitcnt lgkmcnt(0)
	v_add_f32_e32 v14, v14, v52
	ds_bpermute_b32 v52, v26, v15
	s_waitcnt lgkmcnt(0)
	v_add_f32_e32 v15, v15, v52
	ds_bpermute_b32 v52, v26, v16
	ds_bpermute_b32 v26, v26, v17
	s_waitcnt lgkmcnt(1)
	v_add_f32_e32 v16, v16, v52
	s_waitcnt lgkmcnt(0)
	v_add_f32_e32 v17, v17, v26
	v_xor_b32_e32 v26, 8, v240
	v_cmp_lt_i32_e32 vcc, v26, v48
	s_nop 1
	v_cndmask_b32_e32 v26, v240, v26, vcc
	v_lshlrev_b32_e32 v26, 2, v26
	ds_bpermute_b32 v52, v26, v27
	s_waitcnt lgkmcnt(0)
	v_add_f32_e32 v27, v27, v52
	ds_bpermute_b32 v52, v26, v28
	s_waitcnt lgkmcnt(0)
	v_add_f32_e32 v28, v28, v52
	ds_bpermute_b32 v52, v26, v29
	s_waitcnt lgkmcnt(0)
	v_add_f32_e32 v29, v29, v52
	ds_bpermute_b32 v52, v26, v30
	s_waitcnt lgkmcnt(0)
	v_add_f32_e32 v30, v30, v52
	ds_bpermute_b32 v52, v26, v31
	s_waitcnt lgkmcnt(0)
	v_add_f32_e32 v31, v31, v52
	ds_bpermute_b32 v52, v26, v32
	s_waitcnt lgkmcnt(0)
	v_add_f32_e32 v32, v32, v52
	ds_bpermute_b32 v52, v26, v33
	s_waitcnt lgkmcnt(0)
	v_add_f32_e32 v52, v33, v52
	ds_bpermute_b32 v33, v26, v25
	s_waitcnt lgkmcnt(0)
	v_add_f32_e32 v25, v25, v33
	ds_bpermute_b32 v33, v26, v49
	s_waitcnt lgkmcnt(0)
	v_add_f32_e32 v53, v49, v33
	ds_bpermute_b32 v33, v26, v50
	s_waitcnt lgkmcnt(0)
	v_add_f32_e32 v50, v50, v33
	ds_bpermute_b32 v33, v26, v51
	s_waitcnt lgkmcnt(0)
	v_add_f32_e32 v51, v51, v33
	ds_bpermute_b32 v33, v26, v13
	s_waitcnt lgkmcnt(0)
	v_add_f32_e32 v13, v13, v33
	ds_bpermute_b32 v33, v26, v14
	s_waitcnt lgkmcnt(0)
	v_add_f32_e32 v14, v14, v33
	ds_bpermute_b32 v33, v26, v15
	s_waitcnt lgkmcnt(0)
	v_add_f32_e32 v15, v15, v33
	ds_bpermute_b32 v33, v26, v16
	ds_bpermute_b32 v26, v26, v17
	s_waitcnt lgkmcnt(1)
	v_add_f32_e32 v16, v16, v33
	s_waitcnt lgkmcnt(0)
	v_add_f32_e32 v54, v17, v26
	v_xor_b32_e32 v17, 16, v240
	v_cmp_lt_i32_e32 vcc, v17, v48
	s_nop 1
	v_cndmask_b32_e32 v17, v240, v17, vcc
	v_lshlrev_b32_e32 v55, 2, v17
	ds_bpermute_b32 v17, v55, v27
	s_waitcnt lgkmcnt(0)
	v_add_f32_e32 v56, v27, v17
	ds_bpermute_b32 v17, v55, v28
	s_waitcnt lgkmcnt(0)
	v_add_f32_e32 v57, v28, v17
	ds_bpermute_b32 v17, v55, v29
	s_waitcnt lgkmcnt(0)
	v_add_f32_e32 v49, v29, v17
	ds_bpermute_b32 v17, v55, v30
	s_waitcnt lgkmcnt(0)
	v_add_f32_e32 v48, v30, v17
	ds_bpermute_b32 v17, v55, v31
	s_waitcnt lgkmcnt(0)
	v_add_f32_e32 v33, v31, v17
	ds_bpermute_b32 v17, v55, v32
	v_fmamk_f32 v33, v33, 0x3c800000, v233
	s_waitcnt lgkmcnt(0)
	v_add_f32_e32 v32, v32, v17
	ds_bpermute_b32 v17, v55, v52
	v_fmamk_f32 v32, v32, 0x3c800000, v233
	s_waitcnt lgkmcnt(0)
	v_add_f32_e32 v31, v52, v17
	ds_bpermute_b32 v17, v55, v25
	v_fmamk_f32 v31, v31, 0x3c800000, v233
	s_waitcnt lgkmcnt(0)
	v_add_f32_e32 v30, v25, v17
	ds_bpermute_b32 v17, v55, v53
	v_fmamk_f32 v30, v30, 0x3c800000, v233
	s_waitcnt lgkmcnt(0)
	v_add_f32_e32 v29, v53, v17
	ds_bpermute_b32 v17, v55, v50
	s_waitcnt lgkmcnt(0)
	v_add_f32_e32 v28, v50, v17
	ds_bpermute_b32 v17, v55, v51
	v_fmamk_f32 v50, v56, 0x3c800000, v233
	v_cmp_gt_f32_e32 vcc, s19, v50
	s_waitcnt lgkmcnt(0)
	v_add_f32_e32 v27, v51, v17
	ds_bpermute_b32 v17, v55, v13
	v_mul_f32_e32 v51, 0x4f800000, v50
	v_cndmask_b32_e32 v50, v50, v51, vcc
	v_sqrt_f32_e32 v51, v50
	s_waitcnt lgkmcnt(0)
	v_add_f32_e32 v26, v13, v17
	ds_bpermute_b32 v13, v55, v14
	v_add_u32_e32 v52, -1, v51
	v_fma_f32 v53, -v52, v51, v50
	v_cmp_ge_f32_e64 s[82:83], 0, v53
	v_add_u32_e32 v53, 1, v51
	s_waitcnt lgkmcnt(0)
	v_add_f32_e32 v25, v14, v13
	ds_bpermute_b32 v13, v55, v15
	v_cndmask_b32_e64 v52, v51, v52, s[82:83]
	v_fma_f32 v51, -v53, v51, v50
	v_cmp_lt_f32_e64 s[82:83], 0, v51
	s_waitcnt lgkmcnt(0)
	v_add_f32_e32 v17, v15, v13
	ds_bpermute_b32 v13, v55, v16
	v_or_b32_e32 v15, s24, v181
	v_cndmask_b32_e64 v51, v52, v53, s[82:83]
	v_mul_f32_e32 v52, 0x37800000, v51
	v_cndmask_b32_e32 v51, v51, v52, vcc
	s_waitcnt lgkmcnt(0)
	v_add_f32_e32 v14, v16, v13
	v_lshlrev_b32_e32 v16, 2, v15
	global_load_dword v15, v16, s[44:45]
	s_nop 0
	global_load_dword v16, v16, s[44:45] offset:128
	v_cmp_class_f32_e32 vcc, v50, v234
	ds_bpermute_b32 v13, v55, v54
	s_waitcnt lgkmcnt(0)
	v_add_f32_e32 v13, v54, v13
	v_cndmask_b32_e32 v50, v51, v50, vcc
	v_div_scale_f32 v51, s[2:3], v50, v50, 1.0
	v_rcp_f32_e32 v52, v51
	s_nop 0
	v_fma_f32 v53, -v51, v52, 1.0
	v_fmac_f32_e32 v52, v53, v52
	v_div_scale_f32 v53, vcc, 1.0, v50, 1.0
	v_mul_f32_e32 v54, v53, v52
	v_fma_f32 v55, -v51, v54, v53
	v_fmac_f32_e32 v54, v55, v52
	v_fma_f32 v51, -v51, v54, v53
	v_div_fmas_f32 v51, v51, v52, v54
	v_div_fixup_f32 v50, v51, v50, 1.0
	v_mul_f32_e32 v47, v47, v50
	v_mul_f32_e32 v46, v46, v50
	s_waitcnt vmcnt(1)
	v_mul_f32_e32 v47, v47, v15
	v_bfe_u32 v51, v47, 16, 1
	v_add3_u32 v47, v47, v51, s22
	s_waitcnt vmcnt(0)
	v_mul_f32_e32 v46, v46, v16
	ds_write_b16_d16_hi v235, v47
	v_bfe_u32 v47, v46, 16, 1
	v_add3_u32 v46, v46, v47, s22
	ds_write_b16_d16_hi v235, v46 offset:64
	v_fmamk_f32 v46, v57, 0x3c800000, v233
	v_cmp_gt_f32_e32 vcc, s19, v46
	v_mul_f32_e32 v47, 0x4f800000, v46
	s_nop 0
	v_cndmask_b32_e32 v46, v46, v47, vcc
	v_sqrt_f32_e32 v47, v46
	s_nop 0
	v_add_u32_e32 v50, -1, v47
	v_fma_f32 v51, -v50, v47, v46
	v_cmp_ge_f32_e64 s[82:83], 0, v51
	v_add_u32_e32 v51, 1, v47
	s_nop 0
	v_cndmask_b32_e64 v50, v47, v50, s[82:83]
	v_fma_f32 v47, -v51, v47, v46
	v_cmp_lt_f32_e64 s[82:83], 0, v47
	s_nop 1
	v_cndmask_b32_e64 v47, v50, v51, s[82:83]
	v_mul_f32_e32 v50, 0x37800000, v47
	v_cndmask_b32_e32 v47, v47, v50, vcc
	v_cmp_class_f32_e32 vcc, v46, v234
	s_nop 1
	v_cndmask_b32_e32 v46, v47, v46, vcc
	v_div_scale_f32 v47, s[2:3], v46, v46, 1.0
	v_rcp_f32_e32 v50, v47
	s_nop 0
	v_fma_f32 v51, -v47, v50, 1.0
	v_fmac_f32_e32 v50, v51, v50
	v_div_scale_f32 v51, vcc, 1.0, v46, 1.0
	v_mul_f32_e32 v52, v51, v50
	v_fma_f32 v53, -v47, v52, v51
	v_fmac_f32_e32 v52, v53, v50
	v_fma_f32 v47, -v47, v52, v51
	v_div_fmas_f32 v47, v47, v50, v52
	v_div_fixup_f32 v46, v47, v46, 1.0
	v_mul_f32_e32 v45, v45, v46
	v_mul_f32_e32 v45, v45, v15
	v_bfe_u32 v47, v45, 16, 1
	v_mul_f32_e32 v44, v44, v46
	v_add3_u32 v45, v45, v47, s22
	v_mul_f32_e32 v44, v44, v16
	ds_write_b16_d16_hi v235, v45 offset:128
	v_bfe_u32 v45, v44, 16, 1
	v_add3_u32 v44, v44, v45, s22
	ds_write_b16_d16_hi v235, v44 offset:192
	v_fmamk_f32 v44, v49, 0x3c800000, v233
	v_cmp_gt_f32_e32 vcc, s19, v44
	v_mul_f32_e32 v45, 0x4f800000, v44
	s_nop 0
	v_cndmask_b32_e32 v44, v44, v45, vcc
	v_sqrt_f32_e32 v45, v44
	s_nop 0
	v_add_u32_e32 v46, -1, v45
	v_fma_f32 v47, -v46, v45, v44
	v_cmp_ge_f32_e64 s[82:83], 0, v47
	v_add_u32_e32 v47, 1, v45
	s_nop 0
	v_cndmask_b32_e64 v46, v45, v46, s[82:83]
	v_fma_f32 v45, -v47, v45, v44
	v_cmp_lt_f32_e64 s[82:83], 0, v45
	s_nop 1
	v_cndmask_b32_e64 v45, v46, v47, s[82:83]
	v_mul_f32_e32 v46, 0x37800000, v45
	v_cndmask_b32_e32 v45, v45, v46, vcc
	v_cmp_class_f32_e32 vcc, v44, v234
	s_nop 1
	v_cndmask_b32_e32 v44, v45, v44, vcc
	v_div_scale_f32 v45, s[2:3], v44, v44, 1.0
	v_rcp_f32_e32 v46, v45
	s_nop 0
	v_fma_f32 v47, -v45, v46, 1.0
	v_fmac_f32_e32 v46, v47, v46
	v_div_scale_f32 v47, vcc, 1.0, v44, 1.0
	v_mul_f32_e32 v49, v47, v46
	v_fma_f32 v50, -v45, v49, v47
	v_fmac_f32_e32 v49, v50, v46
	v_fma_f32 v45, -v45, v49, v47
	v_div_fmas_f32 v45, v45, v46, v49
	v_div_fixup_f32 v44, v45, v44, 1.0
	v_mul_f32_e32 v43, v43, v44
	v_mul_f32_e32 v43, v43, v15
	v_bfe_u32 v45, v43, 16, 1
	v_mul_f32_e32 v42, v42, v44
	v_add3_u32 v43, v43, v45, s22
	v_mul_f32_e32 v42, v42, v16
	ds_write_b16_d16_hi v235, v43 offset:256
	v_bfe_u32 v43, v42, 16, 1
	v_add3_u32 v42, v42, v43, s22
	ds_write_b16_d16_hi v235, v42 offset:320
	v_fmamk_f32 v42, v48, 0x3c800000, v233
	v_cmp_gt_f32_e32 vcc, s19, v42
	v_mul_f32_e32 v43, 0x4f800000, v42
	s_nop 0
	v_cndmask_b32_e32 v42, v42, v43, vcc
	v_sqrt_f32_e32 v43, v42
	s_nop 0
	v_add_u32_e32 v44, -1, v43
	v_fma_f32 v45, -v44, v43, v42
	v_cmp_ge_f32_e64 s[82:83], 0, v45
	v_add_u32_e32 v45, 1, v43
	s_nop 0
	v_cndmask_b32_e64 v44, v43, v44, s[82:83]
	v_fma_f32 v43, -v45, v43, v42
	v_cmp_lt_f32_e64 s[82:83], 0, v43
	s_nop 1
	v_cndmask_b32_e64 v43, v44, v45, s[82:83]
	v_mul_f32_e32 v44, 0x37800000, v43
	v_cndmask_b32_e32 v43, v43, v44, vcc
	v_cmp_class_f32_e32 vcc, v42, v234
	s_nop 1
	v_cndmask_b32_e32 v42, v43, v42, vcc
	v_div_scale_f32 v43, s[2:3], v42, v42, 1.0
	v_rcp_f32_e32 v44, v43
	s_nop 0
	v_fma_f32 v45, -v43, v44, 1.0
	v_fmac_f32_e32 v44, v45, v44
	v_div_scale_f32 v45, vcc, 1.0, v42, 1.0
	v_mul_f32_e32 v46, v45, v44
	v_fma_f32 v47, -v43, v46, v45
	v_fmac_f32_e32 v46, v47, v44
	v_fma_f32 v43, -v43, v46, v45
	v_div_fmas_f32 v43, v43, v44, v46
	v_div_fixup_f32 v42, v43, v42, 1.0
	v_mul_f32_e32 v41, v41, v42
	v_mul_f32_e32 v41, v41, v15
	v_bfe_u32 v43, v41, 16, 1
	v_mul_f32_e32 v40, v40, v42
	v_add3_u32 v41, v41, v43, s22
	v_mul_f32_e32 v40, v40, v16
	ds_write_b16_d16_hi v235, v41 offset:384
	v_bfe_u32 v41, v40, 16, 1
	v_add3_u32 v40, v40, v41, s22
	ds_write_b16_d16_hi v235, v40 offset:448
	v_cmp_gt_f32_e32 vcc, s19, v33
	v_mul_f32_e32 v40, 0x4f800000, v33
	s_nop 0
	v_cndmask_b32_e32 v33, v33, v40, vcc
	v_sqrt_f32_e32 v40, v33
	s_nop 0
	v_add_u32_e32 v41, -1, v40
	v_fma_f32 v42, -v41, v40, v33
	v_cmp_ge_f32_e64 s[82:83], 0, v42
	v_add_u32_e32 v42, 1, v40
	s_nop 0
	v_cndmask_b32_e64 v41, v40, v41, s[82:83]
	v_fma_f32 v40, -v42, v40, v33
	v_cmp_lt_f32_e64 s[82:83], 0, v40
	s_nop 1
	v_cndmask_b32_e64 v40, v41, v42, s[82:83]
	v_mul_f32_e32 v41, 0x37800000, v40
	v_cndmask_b32_e32 v40, v40, v41, vcc
	v_cmp_class_f32_e32 vcc, v33, v234
	s_nop 1
	v_cndmask_b32_e32 v33, v40, v33, vcc
	v_div_scale_f32 v40, s[2:3], v33, v33, 1.0
	v_rcp_f32_e32 v41, v40
	s_nop 0
	v_fma_f32 v42, -v40, v41, 1.0
	v_fmac_f32_e32 v41, v42, v41
	v_div_scale_f32 v42, vcc, 1.0, v33, 1.0
	v_mul_f32_e32 v43, v42, v41
	v_fma_f32 v44, -v40, v43, v42
	v_fmac_f32_e32 v43, v44, v41
	v_fma_f32 v40, -v40, v43, v42
	v_div_fmas_f32 v40, v40, v41, v43
	v_div_fixup_f32 v33, v40, v33, 1.0
	v_mul_f32_e32 v39, v39, v33
	v_mul_f32_e32 v33, v38, v33
	v_mul_f32_e32 v33, v33, v16
	v_bfe_u32 v38, v33, 16, 1
	v_add3_u32 v33, v33, v38, s22
	ds_write_b16_d16_hi v235, v33 offset:1088
	v_cmp_gt_f32_e32 vcc, s19, v32
	v_mul_f32_e32 v33, 0x4f800000, v32
	v_mul_f32_e32 v39, v39, v15
	v_cndmask_b32_e32 v32, v32, v33, vcc
	v_sqrt_f32_e32 v33, v32
	v_bfe_u32 v40, v39, 16, 1
	v_add3_u32 v39, v39, v40, s22
	ds_write_b16_d16_hi v235, v39 offset:1024
	v_add_u32_e32 v38, -1, v33
	v_fma_f32 v39, -v38, v33, v32
	v_cmp_ge_f32_e64 s[82:83], 0, v39
	v_add_u32_e32 v39, 1, v33
	s_nop 0
	v_cndmask_b32_e64 v38, v33, v38, s[82:83]
	v_fma_f32 v33, -v39, v33, v32
	v_cmp_lt_f32_e64 s[82:83], 0, v33
	s_nop 1
	v_cndmask_b32_e64 v33, v38, v39, s[82:83]
	v_mul_f32_e32 v38, 0x37800000, v33
	v_cndmask_b32_e32 v33, v33, v38, vcc
	v_cmp_class_f32_e32 vcc, v32, v234
	s_nop 1
	v_cndmask_b32_e32 v32, v33, v32, vcc
	v_div_scale_f32 v33, s[2:3], v32, v32, 1.0
	v_rcp_f32_e32 v38, v33
	s_nop 0
	v_fma_f32 v39, -v33, v38, 1.0
	v_fmac_f32_e32 v38, v39, v38
	v_div_scale_f32 v39, vcc, 1.0, v32, 1.0
	v_mul_f32_e32 v40, v39, v38
	v_fma_f32 v41, -v33, v40, v39
	v_fmac_f32_e32 v40, v41, v38
	v_fma_f32 v33, -v33, v40, v39
	v_div_fmas_f32 v33, v33, v38, v40
	v_div_fixup_f32 v32, v33, v32, 1.0
	v_mul_f32_e32 v33, v37, v32
	v_mul_f32_e32 v33, v33, v15
	v_bfe_u32 v37, v33, 16, 1
	v_mul_f32_e32 v32, v36, v32
	v_add3_u32 v33, v33, v37, s22
	v_mul_f32_e32 v32, v32, v16
	ds_write_b16_d16_hi v235, v33 offset:1152
	v_bfe_u32 v33, v32, 16, 1
	v_add3_u32 v32, v32, v33, s22
	ds_write_b16_d16_hi v235, v32 offset:1216
	v_cmp_gt_f32_e32 vcc, s19, v31
	v_mul_f32_e32 v32, 0x4f800000, v31
	s_nop 0
	v_cndmask_b32_e32 v31, v31, v32, vcc
	v_sqrt_f32_e32 v32, v31
	s_nop 0
	v_add_u32_e32 v33, -1, v32
	v_fma_f32 v36, -v33, v32, v31
	v_cmp_ge_f32_e64 s[82:83], 0, v36
	v_add_u32_e32 v36, 1, v32
	s_nop 0
	v_cndmask_b32_e64 v33, v32, v33, s[82:83]
	v_fma_f32 v32, -v36, v32, v31
	v_cmp_lt_f32_e64 s[82:83], 0, v32
	s_nop 1
	v_cndmask_b32_e64 v32, v33, v36, s[82:83]
	v_mul_f32_e32 v33, 0x37800000, v32
	v_cndmask_b32_e32 v32, v32, v33, vcc
	v_cmp_class_f32_e32 vcc, v31, v234
	s_nop 1
	v_cndmask_b32_e32 v31, v32, v31, vcc
	v_div_scale_f32 v32, s[2:3], v31, v31, 1.0
	v_rcp_f32_e32 v33, v32
	s_nop 0
	v_fma_f32 v36, -v32, v33, 1.0
	v_fmac_f32_e32 v33, v36, v33
	v_div_scale_f32 v36, vcc, 1.0, v31, 1.0
	v_mul_f32_e32 v37, v36, v33
	v_fma_f32 v38, -v32, v37, v36
	v_fmac_f32_e32 v37, v38, v33
	v_fma_f32 v32, -v32, v37, v36
	v_div_fmas_f32 v32, v32, v33, v37
	v_div_fixup_f32 v31, v32, v31, 1.0
	v_mul_f32_e32 v32, v35, v31
	v_mul_f32_e32 v32, v32, v15
	v_bfe_u32 v33, v32, 16, 1
	v_mul_f32_e32 v31, v34, v31
	v_add3_u32 v32, v32, v33, s22
	v_mul_f32_e32 v31, v31, v16
	ds_write_b16_d16_hi v235, v32 offset:1280
	v_bfe_u32 v32, v31, 16, 1
	v_add3_u32 v31, v31, v32, s22
	ds_write_b16_d16_hi v235, v31 offset:1344
	v_cmp_gt_f32_e32 vcc, s19, v30
	v_mul_f32_e32 v31, 0x4f800000, v30
	s_nop 0
	v_cndmask_b32_e32 v30, v30, v31, vcc
	v_sqrt_f32_e32 v31, v30
	s_nop 0
	v_add_u32_e32 v32, -1, v31
	v_fma_f32 v33, -v32, v31, v30
	v_cmp_ge_f32_e64 s[82:83], 0, v33
	v_add_u32_e32 v33, 1, v31
	s_nop 0
	v_cndmask_b32_e64 v32, v31, v32, s[82:83]
	v_fma_f32 v31, -v33, v31, v30
	v_cmp_lt_f32_e64 s[82:83], 0, v31
	s_nop 1
	v_cndmask_b32_e64 v31, v32, v33, s[82:83]
	v_mul_f32_e32 v32, 0x37800000, v31
	v_cndmask_b32_e32 v31, v31, v32, vcc
	v_cmp_class_f32_e32 vcc, v30, v234
	s_nop 1
	v_cndmask_b32_e32 v30, v31, v30, vcc
	v_div_scale_f32 v31, s[2:3], v30, v30, 1.0
	v_rcp_f32_e32 v32, v31
	s_nop 0
	v_fma_f32 v33, -v31, v32, 1.0
	v_fmac_f32_e32 v32, v33, v32
	v_div_scale_f32 v33, vcc, 1.0, v30, 1.0
	v_mul_f32_e32 v34, v33, v32
	v_fma_f32 v35, -v31, v34, v33
	v_fmac_f32_e32 v34, v35, v32
	v_fma_f32 v31, -v31, v34, v33
	v_div_fmas_f32 v31, v31, v32, v34
	v_div_fixup_f32 v30, v31, v30, 1.0
	v_mul_f32_e32 v24, v24, v30
	v_mul_f32_e32 v24, v24, v15
	v_bfe_u32 v31, v24, 16, 1
	v_mul_f32_e32 v23, v23, v30
	v_add3_u32 v24, v24, v31, s22
	v_mul_f32_e32 v23, v23, v16
	ds_write_b16_d16_hi v235, v24 offset:1408
	v_bfe_u32 v24, v23, 16, 1
	v_add3_u32 v23, v23, v24, s22
	ds_write_b16_d16_hi v235, v23 offset:1472
	v_fmamk_f32 v23, v29, 0x3c800000, v233
	v_cmp_gt_f32_e32 vcc, s19, v23
	v_mul_f32_e32 v24, 0x4f800000, v23
	s_nop 0
	v_cndmask_b32_e32 v23, v23, v24, vcc
	v_sqrt_f32_e32 v24, v23
	s_nop 0
	v_add_u32_e32 v29, -1, v24
	v_fma_f32 v30, -v29, v24, v23
	v_cmp_ge_f32_e64 s[82:83], 0, v30
	v_add_u32_e32 v30, 1, v24
	s_nop 0
	v_cndmask_b32_e64 v29, v24, v29, s[82:83]
	v_fma_f32 v24, -v30, v24, v23
	v_cmp_lt_f32_e64 s[82:83], 0, v24
	s_nop 1
	v_cndmask_b32_e64 v24, v29, v30, s[82:83]
	v_mul_f32_e32 v29, 0x37800000, v24
	v_cndmask_b32_e32 v24, v24, v29, vcc
	v_cmp_class_f32_e32 vcc, v23, v234
	s_nop 1
	v_cndmask_b32_e32 v23, v24, v23, vcc
	v_div_scale_f32 v24, s[2:3], v23, v23, 1.0
	v_rcp_f32_e32 v29, v24
	s_nop 0
	v_fma_f32 v30, -v24, v29, 1.0
	v_fmac_f32_e32 v29, v30, v29
	v_div_scale_f32 v30, vcc, 1.0, v23, 1.0
	v_mul_f32_e32 v31, v30, v29
	v_fma_f32 v32, -v24, v31, v30
	v_fmac_f32_e32 v31, v32, v29
	v_fma_f32 v24, -v24, v31, v30
	v_div_fmas_f32 v24, v24, v29, v31
	v_div_fixup_f32 v23, v24, v23, 1.0
	v_mul_f32_e32 v22, v22, v23
	v_mul_f32_e32 v22, v22, v15
	v_bfe_u32 v24, v22, 16, 1
	v_mul_f32_e32 v21, v21, v23
	v_add3_u32 v22, v22, v24, s22
	v_mul_f32_e32 v21, v21, v16
	ds_write_b16_d16_hi v235, v22 offset:2048
	v_bfe_u32 v22, v21, 16, 1
	v_add3_u32 v21, v21, v22, s22
	ds_write_b16_d16_hi v235, v21 offset:2112
	v_fmamk_f32 v21, v28, 0x3c800000, v233
	v_cmp_gt_f32_e32 vcc, s19, v21
	v_mul_f32_e32 v22, 0x4f800000, v21
	s_nop 0
	v_cndmask_b32_e32 v21, v21, v22, vcc
	v_sqrt_f32_e32 v22, v21
	s_nop 0
	v_add_u32_e32 v23, -1, v22
	v_fma_f32 v24, -v23, v22, v21
	v_cmp_ge_f32_e64 s[82:83], 0, v24
	v_add_u32_e32 v24, 1, v22
	s_nop 0
	v_cndmask_b32_e64 v23, v22, v23, s[82:83]
	v_fma_f32 v22, -v24, v22, v21
	v_cmp_lt_f32_e64 s[82:83], 0, v22
	s_nop 1
	v_cndmask_b32_e64 v22, v23, v24, s[82:83]
	v_mul_f32_e32 v23, 0x37800000, v22
	v_cndmask_b32_e32 v22, v22, v23, vcc
	v_cmp_class_f32_e32 vcc, v21, v234
	s_nop 1
	v_cndmask_b32_e32 v21, v22, v21, vcc
	v_div_scale_f32 v22, s[2:3], v21, v21, 1.0
	v_rcp_f32_e32 v23, v22
	s_nop 0
	v_fma_f32 v24, -v22, v23, 1.0
	v_fmac_f32_e32 v23, v24, v23
	v_div_scale_f32 v24, vcc, 1.0, v21, 1.0
	v_mul_f32_e32 v28, v24, v23
	v_fma_f32 v29, -v22, v28, v24
	v_fmac_f32_e32 v28, v29, v23
	v_fma_f32 v22, -v22, v28, v24
	v_div_fmas_f32 v22, v22, v23, v28
	v_div_fixup_f32 v21, v22, v21, 1.0
	v_mul_f32_e32 v20, v20, v21
	v_mul_f32_e32 v20, v15, v20
	v_bfe_u32 v22, v20, 16, 1
	v_mul_f32_e32 v19, v19, v21
	v_add3_u32 v20, v20, v22, s22
	v_mul_f32_e32 v19, v19, v16
	ds_write_b16_d16_hi v235, v20 offset:2176
	v_bfe_u32 v20, v19, 16, 1
	v_add3_u32 v19, v19, v20, s22
	ds_write_b16_d16_hi v235, v19 offset:2240
	v_fmamk_f32 v19, v27, 0x3c800000, v233
	v_cmp_gt_f32_e32 vcc, s19, v19
	v_mul_f32_e32 v20, 0x4f800000, v19
	s_nop 0
	v_cndmask_b32_e32 v19, v19, v20, vcc
	v_sqrt_f32_e32 v20, v19
	s_nop 0
	v_add_u32_e32 v21, -1, v20
	v_fma_f32 v22, -v21, v20, v19
	v_cmp_ge_f32_e64 s[82:83], 0, v22
	v_add_u32_e32 v22, 1, v20
	s_nop 0
	v_cndmask_b32_e64 v21, v20, v21, s[82:83]
	v_fma_f32 v20, -v22, v20, v19
	v_cmp_lt_f32_e64 s[82:83], 0, v20
	s_nop 1
	v_cndmask_b32_e64 v20, v21, v22, s[82:83]
	v_mul_f32_e32 v21, 0x37800000, v20
	v_cndmask_b32_e32 v20, v20, v21, vcc
	v_cmp_class_f32_e32 vcc, v19, v234
	s_nop 1
	v_cndmask_b32_e32 v19, v20, v19, vcc
	v_div_scale_f32 v20, s[2:3], v19, v19, 1.0
	v_rcp_f32_e32 v21, v20
	s_nop 0
	v_fma_f32 v22, -v20, v21, 1.0
	v_fmac_f32_e32 v21, v22, v21
	v_div_scale_f32 v22, vcc, 1.0, v19, 1.0
	v_mul_f32_e32 v23, v22, v21
	v_fma_f32 v24, -v20, v23, v22
	v_fmac_f32_e32 v23, v24, v21
	v_fma_f32 v20, -v20, v23, v22
	v_div_fmas_f32 v20, v20, v21, v23
	v_div_fixup_f32 v19, v20, v19, 1.0
	v_mul_f32_e32 v18, v18, v19
	v_mul_f32_e32 v18, v15, v18
	v_bfe_u32 v20, v18, 16, 1
	v_mul_f32_e32 v11, v11, v19
	v_add3_u32 v18, v18, v20, s22
	v_mul_f32_e32 v11, v16, v11
	ds_write_b16_d16_hi v235, v18 offset:2304
	v_bfe_u32 v18, v11, 16, 1
	v_add3_u32 v11, v11, v18, s22
	ds_write_b16_d16_hi v235, v11 offset:2368
	v_fmamk_f32 v11, v26, 0x3c800000, v233
	v_cmp_gt_f32_e32 vcc, s19, v11
	v_mul_f32_e32 v18, 0x4f800000, v11
	s_nop 0
	v_cndmask_b32_e32 v11, v11, v18, vcc
	v_sqrt_f32_e32 v18, v11
	s_nop 0
	v_add_u32_e32 v19, -1, v18
	v_fma_f32 v20, -v19, v18, v11
	v_cmp_ge_f32_e64 s[82:83], 0, v20
	v_add_u32_e32 v20, 1, v18
	s_nop 0
	v_cndmask_b32_e64 v19, v18, v19, s[82:83]
	v_fma_f32 v18, -v20, v18, v11
	v_cmp_lt_f32_e64 s[82:83], 0, v18
	s_nop 1
	v_cndmask_b32_e64 v18, v19, v20, s[82:83]
	v_mul_f32_e32 v19, 0x37800000, v18
	v_cndmask_b32_e32 v18, v18, v19, vcc
	v_cmp_class_f32_e32 vcc, v11, v234
	s_nop 1
	v_cndmask_b32_e32 v11, v18, v11, vcc
	v_div_scale_f32 v18, s[2:3], v11, v11, 1.0
	v_rcp_f32_e32 v19, v18
	s_nop 0
	v_fma_f32 v20, -v18, v19, 1.0
	v_fmac_f32_e32 v19, v20, v19
	v_div_scale_f32 v20, vcc, 1.0, v11, 1.0
	v_mul_f32_e32 v21, v20, v19
	v_fma_f32 v22, -v18, v21, v20
	v_fmac_f32_e32 v21, v22, v19
	v_fma_f32 v18, -v18, v21, v20
	v_div_fmas_f32 v18, v18, v19, v21
	v_div_fixup_f32 v11, v18, v11, 1.0
	v_mul_f32_e32 v7, v7, v11
	v_mul_f32_e32 v7, v15, v7
	v_bfe_u32 v18, v7, 16, 1
	v_mul_f32_e32 v6, v6, v11
	v_add3_u32 v7, v7, v18, s22
	v_mul_f32_e32 v6, v16, v6
	ds_write_b16_d16_hi v235, v7 offset:2432
	v_bfe_u32 v7, v6, 16, 1
	v_add3_u32 v6, v6, v7, s22
	ds_write_b16_d16_hi v235, v6 offset:2496
	v_fmamk_f32 v6, v25, 0x3c800000, v233
	v_cmp_gt_f32_e32 vcc, s19, v6
	v_mul_f32_e32 v7, 0x4f800000, v6
	s_nop 0
	v_cndmask_b32_e32 v6, v6, v7, vcc
	v_sqrt_f32_e32 v7, v6
	s_nop 0
	v_add_u32_e32 v11, -1, v7
	v_fma_f32 v18, -v11, v7, v6
	v_cmp_ge_f32_e64 s[82:83], 0, v18
	v_add_u32_e32 v18, 1, v7
	s_nop 0
	v_cndmask_b32_e64 v11, v7, v11, s[82:83]
	v_fma_f32 v7, -v18, v7, v6
	v_cmp_lt_f32_e64 s[82:83], 0, v7
	s_nop 1
	v_cndmask_b32_e64 v7, v11, v18, s[82:83]
	v_mul_f32_e32 v11, 0x37800000, v7
	v_cndmask_b32_e32 v7, v7, v11, vcc
	v_cmp_class_f32_e32 vcc, v6, v234
	s_nop 1
	v_cndmask_b32_e32 v6, v7, v6, vcc
	v_div_scale_f32 v7, s[2:3], v6, v6, 1.0
	v_rcp_f32_e32 v11, v7
	s_nop 0
	v_fma_f32 v18, -v7, v11, 1.0
	v_fmac_f32_e32 v11, v18, v11
	v_div_scale_f32 v18, vcc, 1.0, v6, 1.0
	v_mul_f32_e32 v19, v18, v11
	v_fma_f32 v20, -v7, v19, v18
	v_fmac_f32_e32 v19, v20, v11
	v_fma_f32 v7, -v7, v19, v18
	v_div_fmas_f32 v7, v7, v11, v19
	v_div_fixup_f32 v6, v7, v6, 1.0
	v_mul_f32_e32 v7, v12, v6
	v_mul_f32_e32 v7, v15, v7
	v_bfe_u32 v11, v7, 16, 1
	v_mul_f32_e32 v6, v10, v6
	v_add3_u32 v7, v7, v11, s22
	v_mul_f32_e32 v6, v16, v6
	ds_write_b16_d16_hi v235, v7 offset:3072
	v_bfe_u32 v7, v6, 16, 1
	v_add3_u32 v6, v6, v7, s22
	ds_write_b16_d16_hi v235, v6 offset:3136
	v_fmamk_f32 v6, v17, 0x3c800000, v233
	v_cmp_gt_f32_e32 vcc, s19, v6
	v_mul_f32_e32 v7, 0x4f800000, v6
	s_nop 0
	v_cndmask_b32_e32 v6, v6, v7, vcc
	v_sqrt_f32_e32 v7, v6
	s_nop 0
	v_add_u32_e32 v10, -1, v7
	v_fma_f32 v11, -v10, v7, v6
	v_cmp_ge_f32_e64 s[82:83], 0, v11
	v_add_u32_e32 v11, 1, v7
	s_nop 0
	v_cndmask_b32_e64 v10, v7, v10, s[82:83]
	v_fma_f32 v7, -v11, v7, v6
	v_cmp_lt_f32_e64 s[82:83], 0, v7
	s_nop 1
	v_cndmask_b32_e64 v7, v10, v11, s[82:83]
	v_mul_f32_e32 v10, 0x37800000, v7
	v_cndmask_b32_e32 v7, v7, v10, vcc
	v_cmp_class_f32_e32 vcc, v6, v234
	s_nop 1
	v_cndmask_b32_e32 v6, v7, v6, vcc
	v_div_scale_f32 v7, s[2:3], v6, v6, 1.0
	v_rcp_f32_e32 v10, v7
	s_nop 0
	v_fma_f32 v11, -v7, v10, 1.0
	v_fmac_f32_e32 v10, v11, v10
	v_div_scale_f32 v11, vcc, 1.0, v6, 1.0
	v_mul_f32_e32 v12, v11, v10
	v_fma_f32 v17, -v7, v12, v11
	v_fmac_f32_e32 v12, v17, v10
	v_fma_f32 v7, -v7, v12, v11
	v_div_fmas_f32 v7, v7, v10, v12
	v_div_fixup_f32 v6, v7, v6, 1.0
	v_mul_f32_e32 v7, v9, v6
	v_mul_f32_e32 v7, v15, v7
	v_bfe_u32 v9, v7, 16, 1
	v_mul_f32_e32 v6, v8, v6
	v_add3_u32 v7, v7, v9, s22
	v_mul_f32_e32 v6, v16, v6
	ds_write_b16_d16_hi v235, v7 offset:3200
	v_bfe_u32 v7, v6, 16, 1
	v_add3_u32 v6, v6, v7, s22
	ds_write_b16_d16_hi v235, v6 offset:3264
	v_fmamk_f32 v6, v14, 0x3c800000, v233
	v_cmp_gt_f32_e32 vcc, s19, v6
	v_mul_f32_e32 v7, 0x4f800000, v6
	s_nop 0
	v_cndmask_b32_e32 v6, v6, v7, vcc
	v_sqrt_f32_e32 v7, v6
	s_nop 0
	v_add_u32_e32 v8, -1, v7
	v_fma_f32 v9, -v8, v7, v6
	v_cmp_ge_f32_e64 s[82:83], 0, v9
	v_add_u32_e32 v9, 1, v7
	s_nop 0
	v_cndmask_b32_e64 v8, v7, v8, s[82:83]
	v_fma_f32 v7, -v9, v7, v6
	v_cmp_lt_f32_e64 s[82:83], 0, v7
	s_nop 1
	v_cndmask_b32_e64 v7, v8, v9, s[82:83]
	v_mul_f32_e32 v8, 0x37800000, v7
	v_cndmask_b32_e32 v7, v7, v8, vcc
	v_cmp_class_f32_e32 vcc, v6, v234
	s_nop 1
	v_cndmask_b32_e32 v6, v7, v6, vcc
	v_div_scale_f32 v7, s[2:3], v6, v6, 1.0
	v_rcp_f32_e32 v8, v7
	s_nop 0
	v_fma_f32 v9, -v7, v8, 1.0
	v_fmac_f32_e32 v8, v9, v8
	v_div_scale_f32 v9, vcc, 1.0, v6, 1.0
	v_mul_f32_e32 v10, v9, v8
	v_fma_f32 v11, -v7, v10, v9
	v_fmac_f32_e32 v10, v11, v8
	v_fma_f32 v7, -v7, v10, v9
	v_div_fmas_f32 v7, v7, v8, v10
	v_div_fixup_f32 v6, v7, v6, 1.0
	v_mul_f32_e32 v5, v5, v6
	v_mul_f32_e32 v5, v15, v5
	v_bfe_u32 v7, v5, 16, 1
	v_mul_f32_e32 v4, v4, v6
	v_add3_u32 v5, v5, v7, s22
	v_mul_f32_e32 v4, v16, v4
	ds_write_b16_d16_hi v235, v5 offset:3328
	v_bfe_u32 v5, v4, 16, 1
	v_add3_u32 v4, v4, v5, s22
	ds_write_b16_d16_hi v235, v4 offset:3392
	v_fmamk_f32 v4, v13, 0x3c800000, v233
	v_cmp_gt_f32_e32 vcc, s19, v4
	v_mul_f32_e32 v5, 0x4f800000, v4
	s_nop 0
	v_cndmask_b32_e32 v4, v4, v5, vcc
	v_sqrt_f32_e32 v5, v4
	s_nop 0
	v_add_u32_e32 v6, -1, v5
	v_fma_f32 v7, -v6, v5, v4
	v_cmp_ge_f32_e64 s[82:83], 0, v7
	v_add_u32_e32 v7, 1, v5
	s_nop 0
	v_cndmask_b32_e64 v6, v5, v6, s[82:83]
	v_fma_f32 v5, -v7, v5, v4
	v_cmp_lt_f32_e64 s[82:83], 0, v5
	s_nop 1
	v_cndmask_b32_e64 v5, v6, v7, s[82:83]
	v_mul_f32_e32 v6, 0x37800000, v5
	v_cndmask_b32_e32 v5, v5, v6, vcc
	v_cmp_class_f32_e32 vcc, v4, v234
	s_nop 1
	v_cndmask_b32_e32 v4, v5, v4, vcc
	v_div_scale_f32 v5, s[2:3], v4, v4, 1.0
	v_rcp_f32_e32 v6, v5
	s_add_u32 s2, s16, s23
	s_addc_u32 s3, s17, 0
	v_fma_f32 v7, -v5, v6, 1.0
	v_fmac_f32_e32 v6, v7, v6
	v_div_scale_f32 v7, vcc, 1.0, v4, 1.0
	v_mul_f32_e32 v8, v7, v6
	v_fma_f32 v9, -v5, v8, v7
	v_fmac_f32_e32 v8, v9, v6
	v_fma_f32 v5, -v5, v8, v7
	v_div_fmas_f32 v5, v5, v6, v8
	v_div_fixup_f32 v4, v5, v4, 1.0
	v_mul_f32_e32 v3, v3, v4
	v_mul_f32_e32 v3, v15, v3
	v_bfe_u32 v5, v3, 16, 1
	v_mul_f32_e32 v2, v2, v4
	v_add3_u32 v3, v3, v5, s22
	v_mul_f32_e32 v2, v16, v2
	ds_write_b16_d16_hi v235, v3 offset:3456
	v_bfe_u32 v3, v2, 16, 1
	v_add3_u32 v2, v2, v3, s22
	ds_write_b16_d16_hi v235, v2 offset:3520
	s_waitcnt lgkmcnt(0)
	ds_read_b128 v[2:5], v236
	v_mov_b32_e32 v9, s3
	v_or_b32_e32 v8, s2, v176
	v_lshl_add_u64 v[6:7], v[178:179], 0, s[14:15]
	v_lshlrev_b64 v[8:9], 11, v[8:9]
	v_lshl_add_u64 v[8:9], v[6:7], 0, v[8:9]
	s_waitcnt lgkmcnt(0)
	global_store_dwordx4 v[8:9], v[2:5], off
	ds_read_b128 v[2:5], v237
	v_mov_b32_e32 v9, s3
	v_or_b32_e32 v8, s2, v180
	v_lshlrev_b64 v[8:9], 11, v[8:9]
	v_lshl_add_u64 v[8:9], v[6:7], 0, v[8:9]
	s_waitcnt lgkmcnt(0)
	global_store_dwordx4 v[8:9], v[2:5], off
	ds_read_b128 v[2:5], v238
	v_mov_b32_e32 v9, s3
	v_or_b32_e32 v8, s2, v182
	v_lshlrev_b64 v[8:9], 11, v[8:9]
	v_lshl_add_u64 v[8:9], v[6:7], 0, v[8:9]
	s_waitcnt lgkmcnt(0)
	global_store_dwordx4 v[8:9], v[2:5], off
	ds_read_b128 v[2:5], v239
	v_mov_b32_e32 v9, s3
	v_or_b32_e32 v8, s2, v184
	v_lshlrev_b64 v[8:9], 11, v[8:9]
	v_lshl_add_u64 v[6:7], v[6:7], 0, v[8:9]
	s_waitcnt lgkmcnt(0)
	global_store_dwordx4 v[6:7], v[2:5], off
	s_waitcnt lgkmcnt(0)
	s_barrier
	s_mov_b64 s[2:3], 0

.LBB0_653:
	s_barrier
	s_and_saveexec_b64 s[2:3], s[0:1]
	s_cbranch_execz .LBB0_655
	s_cmp_eq_u32 s100, 0
	s_cbranch_scc1 .Lfox_first
	v_mov_b32_e32 v2, v254
	s_branch .Lfox_got
.Lfox_first:
	global_atomic_add v2, v175, v231, s[6:7] sc0
	s_waitcnt vmcnt(0)
.Lfox_got:
	v_mov_b32_e32 v3, s18
	ds_write_b32 v3, v2
